# v33 plus: one extra early L2 write-back per XCD and barrier, started by the workgroup that arrives 6th from last on its XCD while it waits
# speedup vs baseline: 1.0059x; 1.0021x over previous
; __device__ __forceinline__ unsigned xb_ld(unsigned* p)              { return __hip_atomic_load(p, __ATOMIC_RELAXED, __HIP_MEMORY_SCOPE_AGENT); }
; __device__ __forceinline__ unsigned xb_add(unsigned* p, unsigned v) { return __hip_atomic_fetch_add(p, v, __ATOMIC_RELAXED, __HIP_MEMORY_SCOPE_AGENT); }
; #define XB_SPIN(cond, bar) do { unsigned _sp = 0; while (cond) { __builtin_amdgcn_s_sleep(1); \
;     if ((++_sp & 255u) == 0u) { if (xb_ld(&(bar)[XB_TMO])) break; if (_sp > XB_SPIN_CAP) { atomicAdd(&(bar)[XB_TMO], 1u); break; } } } } while (0)
; __device__ __forceinline__ void xcd_barrier(const XcdBarrier& b) {
;     ...
;         unsigned nloc = b.st[0], nx = b.st[1];
;         if (nloc == 0u) { xcd_barrier_complete(bar, b.x, nloc, nx); b.st[0] = nloc; b.st[1] = nx; }
;         const unsigned old = xb_add(&bar[XB_XSUB(b.x)], 1u);
;         const unsigned gen = old / nloc;
;         if (old + 1u == (gen + 1u) * nloc) {
;             __builtin_amdgcn_fence(__ATOMIC_RELEASE, "agent");
;             asm volatile("s_waitcnt vmcnt(0)" ::: "memory");
;             const unsigned og = xb_add(&bar[XB_TOP], 1u);
;             const unsigned tg = og / nx;
;             if (og + 1u == (tg + 1u) * nx) xb_add(&bar[XB_TOPGEN], 1u);
;             else XB_SPIN(xb_ld(&bar[XB_TOPGEN]) == tg, bar);
;             __builtin_amdgcn_fence(__ATOMIC_ACQUIRE, "agent");
;             xb_add(&bar[XB_XGEN(b.x)], 1u);
;             asm volatile("s_waitcnt vmcnt(0)" ::: "memory");
;         } else {
;             XB_SPIN(xb_ld(&bar[XB_XGEN(b.x)]) == gen, bar);
.LBB0_117:
	s_or_b64 exec, exec, s[14:15]
	buffer_inv sc1
	v_cvt_f32_u32_e32 v4, v2
	s_waitcnt vmcnt(1)
	v_readfirstlane_b32 s12, v3
	v_sub_u32_e32 v3, 0, v2
	v_rcp_iflag_f32_e32 v4, v4
	v_add_u32_e32 v5, s12, v1
	v_mul_f32_e32 v4, 0x4f7ffffe, v4
	v_cvt_u32_f32_e32 v4, v4
	v_mul_lo_u32 v1, v3, v4
	v_mul_hi_u32 v1, v4, v1
	v_add_u32_e32 v1, v4, v1
	v_mul_hi_u32 v1, v5, v1
	v_mul_lo_u32 v3, v1, v2
	v_sub_u32_e32 v3, v5, v3
	v_add_u32_e32 v4, 1, v1
	v_cmp_ge_u32_e32 vcc, v3, v2
	s_nop 1
	v_cndmask_b32_e32 v1, v1, v4, vcc
	v_sub_u32_e32 v4, v3, v2
	v_cndmask_b32_e32 v3, v3, v4, vcc
	v_add_u32_e32 v4, 1, v1
	v_cmp_ge_u32_e32 vcc, v3, v2
	v_add_u32_e32 v3, 1, v5
	s_nop 0
	v_cndmask_b32_e32 v1, v1, v4, vcc
	v_mul_lo_u32 v4, v2, v1
	v_add_u32_e32 v2, v4, v2
	v_cmp_ne_u32_e32 vcc, v3, v2
	s_and_saveexec_b64 s[12:13], vcc
	s_xor_b64 s[12:13], exec, s[12:13]
	s_cbranch_execz .LBB0_131
	v_sub_u32_e32 v251, v2, v3
	v_cmp_eq_u32_e32 vcc, 6, v251
	s_cbranch_vccz .Lbar_noearly_0
	buffer_wbl2 sc1
.Lbar_noearly_0:
	s_waitcnt lgkmcnt(0)
	v_mov_b32_e32 v0, 0x2000
	global_load_dword v0, v0, s[10:11] offset:1024 sc1
	s_add_u32 s18, s10, 0x2400
	s_addc_u32 s19, s11, 0
	s_waitcnt vmcnt(0)
	v_cmp_eq_u32_e32 vcc, v0, v1
	s_and_saveexec_b64 s[14:15], vcc
	s_cbranch_execz .LBB0_130
	s_add_u32 s16, s24, 0x4200
	s_addc_u32 s17, s25, 0
	s_mov_b32 s33, 1
	s_mov_b64 s[20:21], 0
	v_mov_b32_e32 v0, 0
	s_branch .LBB0_121

; __device__ __forceinline__ unsigned xb_ld(unsigned* p)              { return __hip_atomic_load(p, __ATOMIC_RELAXED, __HIP_MEMORY_SCOPE_AGENT); }
; __device__ __forceinline__ unsigned xb_add(unsigned* p, unsigned v) { return __hip_atomic_fetch_add(p, v, __ATOMIC_RELAXED, __HIP_MEMORY_SCOPE_AGENT); }
; #define XB_SPIN(cond, bar) do { unsigned _sp = 0; while (cond) { __builtin_amdgcn_s_sleep(1); \
;     if ((++_sp & 255u) == 0u) { if (xb_ld(&(bar)[XB_TMO])) break; if (_sp > XB_SPIN_CAP) { atomicAdd(&(bar)[XB_TMO], 1u); break; } } } } while (0)
; __device__ __forceinline__ void xcd_barrier(const XcdBarrier& b) {
;     ...
;         unsigned nloc = b.st[0], nx = b.st[1];
;         if (nloc == 0u) { xcd_barrier_complete(bar, b.x, nloc, nx); b.st[0] = nloc; b.st[1] = nx; }
;         const unsigned old = xb_add(&bar[XB_XSUB(b.x)], 1u);
;         const unsigned gen = old / nloc;
;         if (old + 1u == (gen + 1u) * nloc) {
;             __builtin_amdgcn_fence(__ATOMIC_RELEASE, "agent");
;             asm volatile("s_waitcnt vmcnt(0)" ::: "memory");
;             const unsigned og = xb_add(&bar[XB_TOP], 1u);
;             const unsigned tg = og / nx;
;             if (og + 1u == (tg + 1u) * nx) xb_add(&bar[XB_TOPGEN], 1u);
;             else XB_SPIN(xb_ld(&bar[XB_TOPGEN]) == tg, bar);
;             __builtin_amdgcn_fence(__ATOMIC_ACQUIRE, "agent");
;             xb_add(&bar[XB_XGEN(b.x)], 1u);
;             asm volatile("s_waitcnt vmcnt(0)" ::: "memory");
;         } else {
;             XB_SPIN(xb_ld(&bar[XB_XGEN(b.x)]) == gen, bar);
.LBB0_328:
	s_or_b64 exec, exec, s[12:13]
	buffer_inv sc1
	v_cvt_f32_u32_e32 v4, v2
	s_waitcnt vmcnt(1)
	v_readfirstlane_b32 s10, v3
	v_sub_u32_e32 v3, 0, v2
	v_rcp_iflag_f32_e32 v4, v4
	v_add_u32_e32 v5, s10, v1
	v_mul_f32_e32 v4, 0x4f7ffffe, v4
	v_cvt_u32_f32_e32 v4, v4
	v_mul_lo_u32 v1, v3, v4
	v_mul_hi_u32 v1, v4, v1
	v_add_u32_e32 v1, v4, v1
	v_mul_hi_u32 v1, v5, v1
	v_mul_lo_u32 v3, v1, v2
	v_sub_u32_e32 v3, v5, v3
	v_add_u32_e32 v4, 1, v1
	v_cmp_ge_u32_e32 vcc, v3, v2
	s_nop 1
	v_cndmask_b32_e32 v1, v1, v4, vcc
	v_sub_u32_e32 v4, v3, v2
	v_cndmask_b32_e32 v3, v3, v4, vcc
	v_add_u32_e32 v4, 1, v1
	v_cmp_ge_u32_e32 vcc, v3, v2
	v_add_u32_e32 v3, 1, v5
	s_nop 0
	v_cndmask_b32_e32 v1, v1, v4, vcc
	v_mul_lo_u32 v4, v2, v1
	v_add_u32_e32 v2, v4, v2
	v_cmp_ne_u32_e32 vcc, v3, v2
	s_and_saveexec_b64 s[10:11], vcc
	s_xor_b64 s[10:11], exec, s[10:11]
	s_cbranch_execz .LBB0_342
	v_sub_u32_e32 v251, v2, v3
	v_cmp_eq_u32_e32 vcc, 6, v251
	s_cbranch_vccz .Lbar_noearly_1
	buffer_wbl2 sc1
.Lbar_noearly_1:
	s_waitcnt lgkmcnt(0)
	v_mov_b32_e32 v0, 0x2000
	global_load_dword v0, v0, s[8:9] offset:1024 sc1
	s_add_u32 s16, s8, 0x2400
	s_addc_u32 s17, s9, 0
	s_waitcnt vmcnt(0)
	v_cmp_eq_u32_e32 vcc, v0, v1
	s_and_saveexec_b64 s[12:13], vcc
	s_cbranch_execz .LBB0_341
	s_add_u32 s14, s24, 0x4200
	s_addc_u32 s15, s25, 0
	s_mov_b32 s30, 1
	s_mov_b64 s[18:19], 0
	v_mov_b32_e32 v0, 0
	s_branch .LBB0_332

; __device__ __forceinline__ unsigned xb_ld(unsigned* p)              { return __hip_atomic_load(p, __ATOMIC_RELAXED, __HIP_MEMORY_SCOPE_AGENT); }
; __device__ __forceinline__ unsigned xb_add(unsigned* p, unsigned v) { return __hip_atomic_fetch_add(p, v, __ATOMIC_RELAXED, __HIP_MEMORY_SCOPE_AGENT); }
; #define XB_SPIN(cond, bar) do { unsigned _sp = 0; while (cond) { __builtin_amdgcn_s_sleep(1); \
;     if ((++_sp & 255u) == 0u) { if (xb_ld(&(bar)[XB_TMO])) break; if (_sp > XB_SPIN_CAP) { atomicAdd(&(bar)[XB_TMO], 1u); break; } } } } while (0)
; __device__ __forceinline__ void xcd_barrier(const XcdBarrier& b) {
;     ...
;         unsigned nloc = b.st[0], nx = b.st[1];
;         if (nloc == 0u) { xcd_barrier_complete(bar, b.x, nloc, nx); b.st[0] = nloc; b.st[1] = nx; }
;         const unsigned old = xb_add(&bar[XB_XSUB(b.x)], 1u);
;         const unsigned gen = old / nloc;
;         if (old + 1u == (gen + 1u) * nloc) {
;             __builtin_amdgcn_fence(__ATOMIC_RELEASE, "agent");
;             asm volatile("s_waitcnt vmcnt(0)" ::: "memory");
;             const unsigned og = xb_add(&bar[XB_TOP], 1u);
;             const unsigned tg = og / nx;
;             if (og + 1u == (tg + 1u) * nx) xb_add(&bar[XB_TOPGEN], 1u);
;             else XB_SPIN(xb_ld(&bar[XB_TOPGEN]) == tg, bar);
;             __builtin_amdgcn_fence(__ATOMIC_ACQUIRE, "agent");
;             xb_add(&bar[XB_XGEN(b.x)], 1u);
;             asm volatile("s_waitcnt vmcnt(0)" ::: "memory");
;         } else {
;             XB_SPIN(xb_ld(&bar[XB_XGEN(b.x)]) == gen, bar);
.LBB0_419:
	s_or_b64 exec, exec, s[22:23]
	buffer_inv sc1
	v_cvt_f32_u32_e32 v4, v2
	s_waitcnt vmcnt(1)
	v_readfirstlane_b32 s11, v3
	v_sub_u32_e32 v3, 0, v2
	v_rcp_iflag_f32_e32 v4, v4
	v_add_u32_e32 v5, s11, v1
	v_mul_f32_e32 v4, 0x4f7ffffe, v4
	v_cvt_u32_f32_e32 v4, v4
	v_mul_lo_u32 v1, v3, v4
	v_mul_hi_u32 v1, v4, v1
	v_add_u32_e32 v1, v4, v1
	v_mul_hi_u32 v1, v5, v1
	v_mul_lo_u32 v3, v1, v2
	v_sub_u32_e32 v3, v5, v3
	v_add_u32_e32 v4, 1, v1
	v_cmp_ge_u32_e32 vcc, v3, v2
	s_nop 1
	v_cndmask_b32_e32 v1, v1, v4, vcc
	v_sub_u32_e32 v4, v3, v2
	v_cndmask_b32_e32 v3, v3, v4, vcc
	v_add_u32_e32 v4, 1, v1
	v_cmp_ge_u32_e32 vcc, v3, v2
	v_add_u32_e32 v3, 1, v5
	s_nop 0
	v_cndmask_b32_e32 v1, v1, v4, vcc
	v_mul_lo_u32 v4, v2, v1
	v_add_u32_e32 v2, v4, v2
	v_cmp_ne_u32_e32 vcc, v3, v2
	s_and_saveexec_b64 s[12:13], vcc
	s_xor_b64 s[22:23], exec, s[12:13]
	s_cbranch_execz .LBB0_433
	v_sub_u32_e32 v251, v2, v3
	v_cmp_eq_u32_e32 vcc, 6, v251
	s_cbranch_vccz .Lbar_noearly_2
	buffer_wbl2 sc1
.Lbar_noearly_2:
	v_readlane_b32 s12, v247, 11
	v_readlane_b32 s13, v247, 12
	s_waitcnt lgkmcnt(0)
	s_nop 3
	global_load_dword v0, v173, s[12:13] sc1
	s_waitcnt vmcnt(0)
	v_cmp_eq_u32_e32 vcc, v0, v1
	s_and_saveexec_b64 s[28:29], vcc
	s_cbranch_execz .LBB0_432
	s_mov_b32 s11, 1
	s_mov_b64 s[36:37], 0
	s_branch .LBB0_423

; __device__ __forceinline__ unsigned xb_ld(unsigned* p)              { return __hip_atomic_load(p, __ATOMIC_RELAXED, __HIP_MEMORY_SCOPE_AGENT); }
; __device__ __forceinline__ unsigned xb_add(unsigned* p, unsigned v) { return __hip_atomic_fetch_add(p, v, __ATOMIC_RELAXED, __HIP_MEMORY_SCOPE_AGENT); }
; #define XB_SPIN(cond, bar) do { unsigned _sp = 0; while (cond) { __builtin_amdgcn_s_sleep(1); \
;     if ((++_sp & 255u) == 0u) { if (xb_ld(&(bar)[XB_TMO])) break; if (_sp > XB_SPIN_CAP) { atomicAdd(&(bar)[XB_TMO], 1u); break; } } } } while (0)
; __device__ __forceinline__ void xcd_barrier(const XcdBarrier& b) {
;     ...
;         unsigned nloc = b.st[0], nx = b.st[1];
;         if (nloc == 0u) { xcd_barrier_complete(bar, b.x, nloc, nx); b.st[0] = nloc; b.st[1] = nx; }
;         const unsigned old = xb_add(&bar[XB_XSUB(b.x)], 1u);
;         const unsigned gen = old / nloc;
;         if (old + 1u == (gen + 1u) * nloc) {
;             __builtin_amdgcn_fence(__ATOMIC_RELEASE, "agent");
;             asm volatile("s_waitcnt vmcnt(0)" ::: "memory");
;             const unsigned og = xb_add(&bar[XB_TOP], 1u);
;             const unsigned tg = og / nx;
;             if (og + 1u == (tg + 1u) * nx) xb_add(&bar[XB_TOPGEN], 1u);
;             else XB_SPIN(xb_ld(&bar[XB_TOPGEN]) == tg, bar);
;             __builtin_amdgcn_fence(__ATOMIC_ACQUIRE, "agent");
;             xb_add(&bar[XB_XGEN(b.x)], 1u);
;             asm volatile("s_waitcnt vmcnt(0)" ::: "memory");
;         } else {
;             XB_SPIN(xb_ld(&bar[XB_XGEN(b.x)]) == gen, bar);
.LBB0_1389:
	s_or_b64 exec, exec, s[22:23]
	buffer_inv sc1
	v_cvt_f32_u32_e32 v4, v2
	s_waitcnt vmcnt(1)
	v_readfirstlane_b32 s6, v3
	v_sub_u32_e32 v3, 0, v2
	v_rcp_iflag_f32_e32 v4, v4
	v_add_u32_e32 v5, s6, v1
	v_mul_f32_e32 v4, 0x4f7ffffe, v4
	v_cvt_u32_f32_e32 v4, v4
	v_mul_lo_u32 v1, v3, v4
	v_mul_hi_u32 v1, v4, v1
	v_add_u32_e32 v1, v4, v1
	v_mul_hi_u32 v1, v5, v1
	v_mul_lo_u32 v3, v1, v2
	v_sub_u32_e32 v3, v5, v3
	v_add_u32_e32 v4, 1, v1
	v_cmp_ge_u32_e32 vcc, v3, v2
	s_nop 1
	v_cndmask_b32_e32 v1, v1, v4, vcc
	v_sub_u32_e32 v4, v3, v2
	v_cndmask_b32_e32 v3, v3, v4, vcc
	v_add_u32_e32 v4, 1, v1
	v_cmp_ge_u32_e32 vcc, v3, v2
	v_add_u32_e32 v3, 1, v5
	s_nop 0
	v_cndmask_b32_e32 v1, v1, v4, vcc
	v_mul_lo_u32 v4, v2, v1
	v_add_u32_e32 v2, v4, v2
	v_cmp_ne_u32_e32 vcc, v3, v2
	s_and_saveexec_b64 s[16:17], vcc
	s_xor_b64 s[22:23], exec, s[16:17]
	s_cbranch_execz .LBB0_1403
	v_sub_u32_e32 v251, v2, v3
	v_cmp_eq_u32_e32 vcc, 6, v251
	s_cbranch_vccz .Lbar_noearly_8
	buffer_wbl2 sc1
.Lbar_noearly_8:
	v_readlane_b32 s16, v247, 11
	v_readlane_b32 s17, v247, 12
	s_waitcnt lgkmcnt(0)
	s_nop 3
	global_load_dword v0, v173, s[16:17] sc1
	s_waitcnt vmcnt(0)
	v_cmp_eq_u32_e32 vcc, v0, v1
	s_and_saveexec_b64 s[28:29], vcc
	s_cbranch_execz .LBB0_1402
	s_mov_b32 s6, 1
	s_mov_b64 s[36:37], 0
	s_branch .LBB0_1393

; __device__ __forceinline__ unsigned xb_ld(unsigned* p)              { return __hip_atomic_load(p, __ATOMIC_RELAXED, __HIP_MEMORY_SCOPE_AGENT); }
; #define XB_SPIN(cond, bar) do { unsigned _sp = 0; while (cond) { __builtin_amdgcn_s_sleep(1); \
;     if ((++_sp & 255u) == 0u) { if (xb_ld(&(bar)[XB_TMO])) break; if (_sp > XB_SPIN_CAP) { atomicAdd(&(bar)[XB_TMO], 1u); break; } } } } while (0)
; __device__ __forceinline__ void xcd_barrier(const XcdBarrier& b) {
;     ...
;             XB_SPIN(xb_ld(&bar[XB_XGEN(b.x)]) == gen, bar);
.Lbar_noearly_9:
	v_readlane_b32 s12, v247, 11
	v_readlane_b32 s13, v247, 12
	s_waitcnt lgkmcnt(0)
	s_nop 3
	global_load_dword v0, v173, s[12:13] sc1
	s_waitcnt vmcnt(0)
	v_cmp_eq_u32_e32 vcc, v0, v1
	s_and_saveexec_b64 s[36:37], vcc
	s_cbranch_execz .LBB0_1554
	s_mov_b32 s11, 1
	s_mov_b64 s[40:41], 0
	s_branch .LBB0_1545

; __device__ __forceinline__ unsigned xb_ld(unsigned* p)              { return __hip_atomic_load(p, __ATOMIC_RELAXED, __HIP_MEMORY_SCOPE_AGENT); }
; __device__ __forceinline__ unsigned xb_add(unsigned* p, unsigned v) { return __hip_atomic_fetch_add(p, v, __ATOMIC_RELAXED, __HIP_MEMORY_SCOPE_AGENT); }
; #define XB_SPIN(cond, bar) do { unsigned _sp = 0; while (cond) { __builtin_amdgcn_s_sleep(1); \
;     if ((++_sp & 255u) == 0u) { if (xb_ld(&(bar)[XB_TMO])) break; if (_sp > XB_SPIN_CAP) { atomicAdd(&(bar)[XB_TMO], 1u); break; } } } } while (0)
; __device__ __forceinline__ void xcd_barrier(const XcdBarrier& b) {
;     ...
;         unsigned nloc = b.st[0], nx = b.st[1];
;         if (nloc == 0u) { xcd_barrier_complete(bar, b.x, nloc, nx); b.st[0] = nloc; b.st[1] = nx; }
;         const unsigned old = xb_add(&bar[XB_XSUB(b.x)], 1u);
;         const unsigned gen = old / nloc;
;         if (old + 1u == (gen + 1u) * nloc) {
;             __builtin_amdgcn_fence(__ATOMIC_RELEASE, "agent");
;             asm volatile("s_waitcnt vmcnt(0)" ::: "memory");
;             const unsigned og = xb_add(&bar[XB_TOP], 1u);
;             const unsigned tg = og / nx;
;             if (og + 1u == (tg + 1u) * nx) xb_add(&bar[XB_TOPGEN], 1u);
;             else XB_SPIN(xb_ld(&bar[XB_TOPGEN]) == tg, bar);
;             __builtin_amdgcn_fence(__ATOMIC_ACQUIRE, "agent");
;             xb_add(&bar[XB_XGEN(b.x)], 1u);
;             asm volatile("s_waitcnt vmcnt(0)" ::: "memory");
;         } else {
;             XB_SPIN(xb_ld(&bar[XB_XGEN(b.x)]) == gen, bar);
.LBB0_2162:
	s_or_b64 exec, exec, s[22:23]
	buffer_inv sc1
	v_cvt_f32_u32_e32 v4, v2
	s_waitcnt vmcnt(1)
	v_readfirstlane_b32 s6, v3
	v_sub_u32_e32 v3, 0, v2
	v_rcp_iflag_f32_e32 v4, v4
	v_add_u32_e32 v5, s6, v1
	v_mul_f32_e32 v4, 0x4f7ffffe, v4
	v_cvt_u32_f32_e32 v4, v4
	v_mul_lo_u32 v1, v3, v4
	v_mul_hi_u32 v1, v4, v1
	v_add_u32_e32 v1, v4, v1
	v_mul_hi_u32 v1, v5, v1
	v_mul_lo_u32 v3, v1, v2
	v_sub_u32_e32 v3, v5, v3
	v_add_u32_e32 v4, 1, v1
	v_cmp_ge_u32_e32 vcc, v3, v2
	s_nop 1
	v_cndmask_b32_e32 v1, v1, v4, vcc
	v_sub_u32_e32 v4, v3, v2
	v_cndmask_b32_e32 v3, v3, v4, vcc
	v_add_u32_e32 v4, 1, v1
	v_cmp_ge_u32_e32 vcc, v3, v2
	v_add_u32_e32 v3, 1, v5
	s_nop 0
	v_cndmask_b32_e32 v1, v1, v4, vcc
	v_mul_lo_u32 v4, v2, v1
	v_add_u32_e32 v2, v4, v2
	v_cmp_ne_u32_e32 vcc, v3, v2
	s_and_saveexec_b64 s[14:15], vcc
	s_xor_b64 s[22:23], exec, s[14:15]
	s_cbranch_execz .LBB0_2176
	v_sub_u32_e32 v251, v2, v3
	v_cmp_eq_u32_e32 vcc, 6, v251
	s_cbranch_vccz .Lbar_noearly_14
	buffer_wbl2 sc1
.Lbar_noearly_14:
	v_readlane_b32 s14, v247, 11
	v_readlane_b32 s15, v247, 12
	s_waitcnt lgkmcnt(0)
	s_nop 3
	global_load_dword v0, v173, s[14:15] sc1
	s_waitcnt vmcnt(0)
	v_cmp_eq_u32_e32 vcc, v0, v1
	s_and_saveexec_b64 s[26:27], vcc
	s_cbranch_execz .LBB0_2175
	s_mov_b32 s6, 1
	s_mov_b64 s[28:29], 0
	s_branch .LBB0_2166

; __device__ __forceinline__ unsigned xb_ld(unsigned* p)              { return __hip_atomic_load(p, __ATOMIC_RELAXED, __HIP_MEMORY_SCOPE_AGENT); }
; __device__ __forceinline__ unsigned xb_add(unsigned* p, unsigned v) { return __hip_atomic_fetch_add(p, v, __ATOMIC_RELAXED, __HIP_MEMORY_SCOPE_AGENT); }
; #define XB_SPIN(cond, bar) do { unsigned _sp = 0; while (cond) { __builtin_amdgcn_s_sleep(1); \
;     if ((++_sp & 255u) == 0u) { if (xb_ld(&(bar)[XB_TMO])) break; if (_sp > XB_SPIN_CAP) { atomicAdd(&(bar)[XB_TMO], 1u); break; } } } } while (0)
; __device__ __forceinline__ void xcd_barrier(const XcdBarrier& b) {
;     ...
;         unsigned nloc = b.st[0], nx = b.st[1];
;         if (nloc == 0u) { xcd_barrier_complete(bar, b.x, nloc, nx); b.st[0] = nloc; b.st[1] = nx; }
;         const unsigned old = xb_add(&bar[XB_XSUB(b.x)], 1u);
;         const unsigned gen = old / nloc;
;         if (old + 1u == (gen + 1u) * nloc) {
;             __builtin_amdgcn_fence(__ATOMIC_RELEASE, "agent");
;             asm volatile("s_waitcnt vmcnt(0)" ::: "memory");
;             const unsigned og = xb_add(&bar[XB_TOP], 1u);
;             const unsigned tg = og / nx;
;             if (og + 1u == (tg + 1u) * nx) xb_add(&bar[XB_TOPGEN], 1u);
;             else XB_SPIN(xb_ld(&bar[XB_TOPGEN]) == tg, bar);
;             __builtin_amdgcn_fence(__ATOMIC_ACQUIRE, "agent");
;             xb_add(&bar[XB_XGEN(b.x)], 1u);
;             asm volatile("s_waitcnt vmcnt(0)" ::: "memory");
;         } else {
;             XB_SPIN(xb_ld(&bar[XB_XGEN(b.x)]) == gen, bar);
.LBB0_2258:
	s_or_b64 exec, exec, s[22:23]
	buffer_inv sc1
	v_cvt_f32_u32_e32 v4, v2
	s_waitcnt vmcnt(1)
	v_readfirstlane_b32 s11, v3
	v_sub_u32_e32 v3, 0, v2
	v_rcp_iflag_f32_e32 v4, v4
	v_add_u32_e32 v5, s11, v1
	v_mul_f32_e32 v4, 0x4f7ffffe, v4
	v_cvt_u32_f32_e32 v4, v4
	v_mul_lo_u32 v1, v3, v4
	v_mul_hi_u32 v1, v4, v1
	v_add_u32_e32 v1, v4, v1
	v_mul_hi_u32 v1, v5, v1
	v_mul_lo_u32 v3, v1, v2
	v_sub_u32_e32 v3, v5, v3
	v_add_u32_e32 v4, 1, v1
	v_cmp_ge_u32_e32 vcc, v3, v2
	s_nop 1
	v_cndmask_b32_e32 v1, v1, v4, vcc
	v_sub_u32_e32 v4, v3, v2
	v_cndmask_b32_e32 v3, v3, v4, vcc
	v_add_u32_e32 v4, 1, v1
	v_cmp_ge_u32_e32 vcc, v3, v2
	v_add_u32_e32 v3, 1, v5
	s_nop 0
	v_cndmask_b32_e32 v1, v1, v4, vcc
	v_mul_lo_u32 v4, v2, v1
	v_add_u32_e32 v2, v4, v2
	v_cmp_ne_u32_e32 vcc, v3, v2
	s_and_saveexec_b64 s[14:15], vcc
	s_xor_b64 s[22:23], exec, s[14:15]
	s_cbranch_execz .LBB0_2272
	v_sub_u32_e32 v251, v2, v3
	v_cmp_eq_u32_e32 vcc, 6, v251
	s_cbranch_vccz .Lbar_noearly_15
	buffer_wbl2 sc1
.Lbar_noearly_15:
	v_readlane_b32 s14, v247, 11
	v_readlane_b32 s15, v247, 12
	s_waitcnt lgkmcnt(0)
	s_nop 3
	global_load_dword v0, v173, s[14:15] sc1
	s_waitcnt vmcnt(0)
	v_cmp_eq_u32_e32 vcc, v0, v1
	s_and_saveexec_b64 s[36:37], vcc
	s_cbranch_execz .LBB0_2271
	s_mov_b32 s11, 1
	s_mov_b64 s[40:41], 0
	s_branch .LBB0_2262

; __device__ __forceinline__ unsigned xb_ld(unsigned* p)              { return __hip_atomic_load(p, __ATOMIC_RELAXED, __HIP_MEMORY_SCOPE_AGENT); }
; #define XB_SPIN(cond, bar) do { unsigned _sp = 0; while (cond) { __builtin_amdgcn_s_sleep(1); \
;     if ((++_sp & 255u) == 0u) { if (xb_ld(&(bar)[XB_TMO])) break; if (_sp > XB_SPIN_CAP) { atomicAdd(&(bar)[XB_TMO], 1u); break; } } } } while (0)
; __device__ __forceinline__ void xcd_barrier(const XcdBarrier& b) {
;     ...
;             XB_SPIN(xb_ld(&bar[XB_XGEN(b.x)]) == gen, bar);
.Lbar_noearly_16:
	v_readlane_b32 s16, v247, 11
	v_readlane_b32 s17, v247, 12
	s_waitcnt lgkmcnt(0)
	s_nop 3
	global_load_dword v0, v173, s[16:17] sc1
	s_waitcnt vmcnt(0)
	v_cmp_eq_u32_e32 vcc, v0, v1
	s_and_saveexec_b64 s[30:31], vcc
	s_cbranch_execz .LBB0_2563
	s_mov_b32 s6, 1
	s_mov_b64 s[36:37], 0
	s_branch .LBB0_2554

; __device__ __forceinline__ unsigned xb_ld(unsigned* p)              { return __hip_atomic_load(p, __ATOMIC_RELAXED, __HIP_MEMORY_SCOPE_AGENT); }
; __device__ __forceinline__ unsigned xb_add(unsigned* p, unsigned v) { return __hip_atomic_fetch_add(p, v, __ATOMIC_RELAXED, __HIP_MEMORY_SCOPE_AGENT); }
; #define XB_SPIN(cond, bar) do { unsigned _sp = 0; while (cond) { __builtin_amdgcn_s_sleep(1); \
;     if ((++_sp & 255u) == 0u) { if (xb_ld(&(bar)[XB_TMO])) break; if (_sp > XB_SPIN_CAP) { atomicAdd(&(bar)[XB_TMO], 1u); break; } } } } while (0)
; __device__ __forceinline__ void xcd_barrier(const XcdBarrier& b) {
;     ...
;         const unsigned old = xb_add(&bar[XB_XSUB(b.x)], 1u);
;         const unsigned gen = old / nloc;
;         if (old + 1u == (gen + 1u) * nloc) {
;             __builtin_amdgcn_fence(__ATOMIC_RELEASE, "agent");
;             asm volatile("s_waitcnt vmcnt(0)" ::: "memory");
;             const unsigned og = xb_add(&bar[XB_TOP], 1u);
;             const unsigned tg = og / nx;
;             if (og + 1u == (tg + 1u) * nx) xb_add(&bar[XB_TOPGEN], 1u);
;             else XB_SPIN(xb_ld(&bar[XB_TOPGEN]) == tg, bar);
;             __builtin_amdgcn_fence(__ATOMIC_ACQUIRE, "agent");
;             xb_add(&bar[XB_XGEN(b.x)], 1u);
;             asm volatile("s_waitcnt vmcnt(0)" ::: "memory");
;         } else {
;             XB_SPIN(xb_ld(&bar[XB_XGEN(b.x)]) == gen, bar);
.LBB0_2618:
	s_or_b64 exec, exec, s[2:3]
	buffer_inv sc1
	v_cvt_f32_u32_e32 v4, v2
	s_waitcnt vmcnt(1)
	v_readfirstlane_b32 s2, v3
	v_sub_u32_e32 v3, 0, v2
	v_rcp_iflag_f32_e32 v4, v4
	v_add_u32_e32 v5, s2, v1
	v_mul_f32_e32 v4, 0x4f7ffffe, v4
	v_cvt_u32_f32_e32 v4, v4
	v_mul_lo_u32 v1, v3, v4
	v_mul_hi_u32 v1, v4, v1
	v_add_u32_e32 v1, v4, v1
	v_mul_hi_u32 v1, v5, v1
	v_mul_lo_u32 v3, v1, v2
	v_sub_u32_e32 v3, v5, v3
	v_add_u32_e32 v4, 1, v1
	v_cmp_ge_u32_e32 vcc, v3, v2
	s_nop 1
	v_cndmask_b32_e32 v1, v1, v4, vcc
	v_sub_u32_e32 v4, v3, v2
	v_cndmask_b32_e32 v3, v3, v4, vcc
	v_add_u32_e32 v4, 1, v1
	v_cmp_ge_u32_e32 vcc, v3, v2
	v_add_u32_e32 v3, 1, v5
	s_nop 0
	v_cndmask_b32_e32 v1, v1, v4, vcc
	v_mul_lo_u32 v4, v2, v1
	v_add_u32_e32 v2, v4, v2
	v_cmp_ne_u32_e32 vcc, v3, v2
	s_and_saveexec_b64 s[2:3], vcc
	s_xor_b64 s[2:3], exec, s[2:3]
	s_cbranch_execz .LBB0_2632
	v_sub_u32_e32 v251, v2, v3
	v_cmp_eq_u32_e32 vcc, 6, v251
	s_cbranch_vccz .Lbar_noearly_17
	buffer_wbl2 sc1
.Lbar_noearly_17:
	v_readlane_b32 s4, v247, 11
	s_waitcnt lgkmcnt(0)
	v_mov_b32_e32 v0, 0
	v_readlane_b32 s5, v247, 12
	s_nop 4
	global_load_dword v2, v0, s[4:5] sc1
	s_waitcnt vmcnt(0)
	v_cmp_eq_u32_e32 vcc, v2, v1
	s_and_saveexec_b64 s[4:5], vcc
	s_cbranch_execz .LBB0_2631
	s_mov_b32 s16, 1
	s_mov_b64 s[6:7], 0
	s_branch .LBB0_2622
